# GU: trailing half takes its offset-restoring barrier after the unit scheduler (scheduler overlaps the leading half's first load segment)
# speedup vs baseline: 1.0121x; 1.0121x over previous
; #define PG8_STAGE(bufoff, gbase, voff) do { _Pragma("unroll") for (int _i = 0; _i < 2; ++_i) \
;         __builtin_amdgcn_global_load_lds((const unsigned*)((const char*)(gbase) + (voff)[_i]), (PG8_LAS unsigned*)(lds + (bufoff) + ldsw + _i * 8192), 16, 0, 0); } while (0)
; #define PG8_WAIT_V(n) asm volatile("s_waitcnt vmcnt(" #n ")" ::: "memory")
; #define PG8_BAR __builtin_amdgcn_s_barrier()
; template <class Epi, class Sched, bool ALIGN_EPI = false, bool SP2 = false>
; __device__ __forceinline__ void gemm_phase(PG8_LAS unsigned char* lds, const Gemm g, const Sched& S, const Epi& E) {
;     ...
;     const int aoff = lds_byte(wr * 64 + fr, fq * 8), boff = lds_byte(wc * 32 + fr, fq * 8);
;     ...
;         PG8_WAIT_V(2); PG8_BAR;
;         PG8_STAGE(PG8_SB(1, 0), cB + kstep, voffB); PG8_STAGE(PG8_SA(1, 0), cA + kstep, voffA); PG8_STAGE(PG8_SB(1, 1), cB + hstep + kstep, voffB);
;         PG8_WAIT_V(6); PG8_BAR;
.LBB0_180:
	s_add_i32 m0, s61, 0x18000
	v_lshl_add_u64 v[8:9], v[8:9], 0, s[20:21]
	s_waitcnt vmcnt(2)
	s_barrier
	global_load_lds_dwordx4 v[8:9], off
	v_lshl_add_u64 v[4:5], v[4:5], 0, s[20:21]
	s_add_i32 m0, s61, 0x1a000
	s_add_i32 s65, s61, 0x8000
	global_load_lds_dwordx4 v[4:5], off
	v_lshl_add_u64 v[4:5], v[6:7], 0, s[20:21]
	s_mov_b32 m0, s65
	s_add_i32 s66, s61, 0xa000
	global_load_lds_dwordx4 v[4:5], off
	v_lshl_add_u64 v[4:5], v[10:11], 0, s[20:21]
	s_mov_b32 m0, s66
	v_lshl_add_u64 v[2:3], v[2:3], 0, s[20:21]
	global_load_lds_dwordx4 v[4:5], off
	s_add_i32 m0, s61, 0x1c000
	v_lshl_add_u64 v[0:1], v[0:1], 0, s[20:21]
	global_load_lds_dwordx4 v[2:3], off
	s_add_i32 m0, s61, 0x1e000
	v_and_b32_e32 v2, 15, v12
	global_load_lds_dwordx4 v[0:1], off
	v_bfe_u32 v1, v12, 4, 2
	s_lshr_b32 s1, s1, 26
	v_lshlrev_b32_e32 v208, 4, v1
	s_add_i32 s1, s0, s1
	v_lshl_or_b32 v147, s39, 6, v2
	v_lshlrev_b32_e32 v0, 3, v1
	v_lshl_or_b32 v1, v2, 6, v208
	v_lshlrev_b32_e32 v2, 2, v12
	s_ashr_i32 s67, s1, 6
	s_lshl_b32 s1, s39, 13
	v_and_b32_e32 v2, 32, v2
	v_bitop3_b32 v3, v1, s1, v2 bitop3:0xde
	s_lshl_b32 s1, s38, 5
	s_and_b32 s1, s1, 0x60
	s_lshl_b32 s38, s1, 7
	v_bitop3_b32 v151, v1, s38, v2 bitop3:0xde
	v_readlane_b32 s38, v252, 38
	s_cmp_gt_i32 s0, 63
	v_readlane_b32 s39, v252, 39
	v_add_u32_e32 v1, v18, v16
	s_waitcnt vmcnt(6)
	s_cselect_b64 s[52:53], -1, 0
	s_add_i32 s68, s67, -2
	v_lshl_add_u64 v[136:137], s[38:39], 0, v[208:209]
	v_add_lshl_u32 v208, v1, v17, 1
	v_add_u32_e32 v1, v15, v13
	s_cmpk_lt_u32 s18, 0x100
	v_lshl_add_u64 v[138:139], s[44:45], 0, v[208:209]
	v_add_lshl_u32 v208, v1, v14, 1
	s_cselect_b64 s[54:55], -1, 0
	v_or_b32_e32 v155, 16, v147
	v_or_b32_e32 v157, 32, v147
	v_or_b32_e32 v159, 48, v147
	s_ashr_i32 s43, s42, 31
	v_lshl_add_u64 v[140:141], s[44:45], 0, v[208:209]
	s_mov_b32 s69, 0
	v_add_u32_e32 v161, 0, v3
	s_lshl_b32 s18, s1, 1
	v_lshlrev_b32_e32 v208, 1, v0
	s_barrier
	s_mov_b32 s92, 0
	s_branch .LBB0_183

; #define PG8_BAR __builtin_amdgcn_s_barrier()
; template <class Epi, class Sched, bool ALIGN_EPI = false, bool SP2 = false>
; __device__ __forceinline__ void gemm_phase(PG8_LAS unsigned char* lds, const Gemm g, const Sched& S, const Epi& E) {
;     ...
;                     for (int n = 0; n < 2; ++n) acc[a][b][m][n] = (f32x4){0.f, 0.f, 0.f, 0.f};
;         cur = nxt; cA = nA; cB = nB; ++ui;
;         if constexpr (ALIGN_EPI) { if (wr == 1) PG8_BAR; }
.LBB0_189:
	s_cmp_eq_u32 s92, 1
	s_cbranch_scc0 .Lgu_no_restore_bar
	s_barrier

; __device__ __forceinline__ u32x2 pack4(const f32x4 v) { u32x2 w; w.x = cvt_pk_bf16(v[0], v[1]); w.y = cvt_pk_bf16(v[2], v[3]); return w; }
;     __device__ __forceinline__ void operator()(const f32x4 (&acc)[2][2][4][2], const Unit& u, int wr, int wc, int fr, int fq) const {
;     ...
;             for (int m = 0; m < 4; ++m) {
;                 const int row = u.pm * BM + ai * HALF + wr * 64 + m * 16 + fr;
;                 const float rs = rsv[ai][m];
;                 u32x2 w[2];
; #pragma unroll
;                 for (int n = 0; n < 2; ++n) {
;                     const f32x4 g = acc[ai][0][m][n] * rs, up = acc[ai][1][m][n] * rs; f32x4 o;
; #pragma unroll
;                     for (int j = 0; j < 4; ++j) { const float e = __builtin_amdgcn_exp2f(-g[j] * kLog2e); o[j] = g[j] * up[j] * __builtin_amdgcn_rcpf(1.0f + e); }
;                     w[n] = pack4(o);
;                 }
;                 *(u32x4_*)(H + (size_t)row * 2816 + u.pn * 128 + wc * 32 + fq * 8) = (u32x4_){w[0].x, w[0].y, w[1].x, w[1].y};
.Lgu_rs_hit:
	s_and_b64 vcc, exec, s[38:39]
	v_mul_u32_u24_e32 v186, 0x1600, v162
	v_mov_b32_e32 v187, 0
	s_lshl_b32 s30, s72, 7
	s_ashr_i32 s31, s30, 31
	s_lshl_b64 s[30:31], s[30:31], 1
	v_lshl_add_u64 v[184:185], s[90:91], 0, v[186:187]
	v_lshl_add_u64 v[184:185], v[184:185], 0, s[30:31]
	v_lshl_add_u64 v[184:185], v[184:185], 0, s[18:19]
	v_lshl_add_u64 v[184:185], v[184:185], 0, v[208:209]
	s_mov_b32 s34, 0x16000
	s_mov_b32 s35, 0
	s_mov_b32 s30, 0x6e000
	s_mov_b32 s31, 0
	v_mul_f32_e32 v180, 0xbfb8aa3b, v164
	v_mul_f32_e32 v182, v164, v164
	v_rcp_f32_e32 v182, v182
	v_pk_mul_f32 v[168:169], v[120:121], v[180:181] op_sel_hi:[1,0]
	v_pk_mul_f32 v[170:171], v[122:123], v[180:181] op_sel_hi:[1,0]
	v_pk_mul_f32 v[172:173], v[116:117], v[180:181] op_sel_hi:[1,0]
	v_pk_mul_f32 v[174:175], v[118:119], v[180:181] op_sel_hi:[1,0]
	v_exp_f32_e32 v168, v168
	v_exp_f32_e32 v169, v169
	v_exp_f32_e32 v170, v170
	v_exp_f32_e32 v171, v171
	v_exp_f32_e32 v172, v172
	v_exp_f32_e32 v173, v173
	v_exp_f32_e32 v174, v174
	v_exp_f32_e32 v175, v175
	v_pk_mul_f32 v[120:121], v[120:121], v[124:125]
	v_pk_mul_f32 v[122:123], v[122:123], v[126:127]
	v_pk_mul_f32 v[116:117], v[116:117], v[112:113]
	v_pk_mul_f32 v[118:119], v[118:119], v[114:115]
	v_pk_fma_f32 v[168:169], v[168:169], v[182:183], v[182:183] op_sel_hi:[1,0,0]
	v_pk_fma_f32 v[170:171], v[170:171], v[182:183], v[182:183] op_sel_hi:[1,0,0]
	v_pk_fma_f32 v[172:173], v[172:173], v[182:183], v[182:183] op_sel_hi:[1,0,0]
	v_pk_fma_f32 v[174:175], v[174:175], v[182:183], v[182:183] op_sel_hi:[1,0,0]
	v_rcp_f32_e32 v168, v168
	v_rcp_f32_e32 v169, v169
	v_rcp_f32_e32 v170, v170
	v_rcp_f32_e32 v171, v171
	v_rcp_f32_e32 v172, v172
	v_rcp_f32_e32 v173, v173
	v_rcp_f32_e32 v174, v174
	v_rcp_f32_e32 v175, v175
	s_nop 0
	v_pk_mul_f32 v[120:121], v[120:121], v[168:169]
	v_pk_mul_f32 v[122:123], v[122:123], v[170:171]
	v_pk_mul_f32 v[116:117], v[116:117], v[172:173]
	v_pk_mul_f32 v[118:119], v[118:119], v[174:175]
	v_cvt_pk_bf16_f32 v176, v120, v121
	v_cvt_pk_bf16_f32 v177, v122, v123
	v_cvt_pk_bf16_f32 v178, v116, v117
	v_cvt_pk_bf16_f32 v179, v118, v119
	global_store_dwordx4 v[184:185], v[176:179], off
	v_lshl_add_u64 v[184:185], v[184:185], 0, s[34:35]
	v_mul_f32_e32 v180, 0xbfb8aa3b, v166
	v_mul_f32_e32 v182, v166, v166
	v_rcp_f32_e32 v182, v182
	v_pk_mul_f32 v[168:169], v[108:109], v[180:181] op_sel_hi:[1,0]
	v_pk_mul_f32 v[170:171], v[110:111], v[180:181] op_sel_hi:[1,0]
	v_pk_mul_f32 v[172:173], v[100:101], v[180:181] op_sel_hi:[1,0]
	v_pk_mul_f32 v[174:175], v[102:103], v[180:181] op_sel_hi:[1,0]
	v_exp_f32_e32 v168, v168
	v_exp_f32_e32 v169, v169
	v_exp_f32_e32 v170, v170
	v_exp_f32_e32 v171, v171
	v_exp_f32_e32 v172, v172
	v_exp_f32_e32 v173, v173
	v_exp_f32_e32 v174, v174
	v_exp_f32_e32 v175, v175
	v_pk_mul_f32 v[108:109], v[108:109], v[104:105]
	v_pk_mul_f32 v[110:111], v[110:111], v[106:107]
	v_pk_mul_f32 v[100:101], v[100:101], v[96:97]
	v_pk_mul_f32 v[102:103], v[102:103], v[98:99]
	v_pk_fma_f32 v[168:169], v[168:169], v[182:183], v[182:183] op_sel_hi:[1,0,0]
	v_pk_fma_f32 v[170:171], v[170:171], v[182:183], v[182:183] op_sel_hi:[1,0,0]
	v_pk_fma_f32 v[172:173], v[172:173], v[182:183], v[182:183] op_sel_hi:[1,0,0]
	v_pk_fma_f32 v[174:175], v[174:175], v[182:183], v[182:183] op_sel_hi:[1,0,0]
	v_rcp_f32_e32 v168, v168
	v_rcp_f32_e32 v169, v169
	v_rcp_f32_e32 v170, v170
	v_rcp_f32_e32 v171, v171
	v_rcp_f32_e32 v172, v172
	v_rcp_f32_e32 v173, v173
	v_rcp_f32_e32 v174, v174
	v_rcp_f32_e32 v175, v175
	s_nop 0
	v_pk_mul_f32 v[108:109], v[108:109], v[168:169]
	v_pk_mul_f32 v[110:111], v[110:111], v[170:171]
	v_pk_mul_f32 v[100:101], v[100:101], v[172:173]
	v_pk_mul_f32 v[102:103], v[102:103], v[174:175]
	v_cvt_pk_bf16_f32 v176, v108, v109
	v_cvt_pk_bf16_f32 v177, v110, v111
	v_cvt_pk_bf16_f32 v178, v100, v101
	v_cvt_pk_bf16_f32 v179, v102, v103
	global_store_dwordx4 v[184:185], v[176:179], off
	v_lshl_add_u64 v[184:185], v[184:185], 0, s[34:35]
	v_mul_f32_e32 v180, 0xbfb8aa3b, v160
	v_mul_f32_e32 v182, v160, v160
	v_rcp_f32_e32 v182, v182
	v_pk_mul_f32 v[168:169], v[92:93], v[180:181] op_sel_hi:[1,0]
	v_pk_mul_f32 v[170:171], v[94:95], v[180:181] op_sel_hi:[1,0]
	v_pk_mul_f32 v[172:173], v[84:85], v[180:181] op_sel_hi:[1,0]
	v_pk_mul_f32 v[174:175], v[86:87], v[180:181] op_sel_hi:[1,0]
	v_exp_f32_e32 v168, v168
	v_exp_f32_e32 v169, v169
	v_exp_f32_e32 v170, v170
	v_exp_f32_e32 v171, v171
	v_exp_f32_e32 v172, v172
	v_exp_f32_e32 v173, v173
	v_exp_f32_e32 v174, v174
	v_exp_f32_e32 v175, v175
	v_pk_mul_f32 v[92:93], v[92:93], v[88:89]
	v_pk_mul_f32 v[94:95], v[94:95], v[90:91]
	v_pk_mul_f32 v[84:85], v[84:85], v[80:81]
	v_pk_mul_f32 v[86:87], v[86:87], v[82:83]
	v_pk_fma_f32 v[168:169], v[168:169], v[182:183], v[182:183] op_sel_hi:[1,0,0]
	v_pk_fma_f32 v[170:171], v[170:171], v[182:183], v[182:183] op_sel_hi:[1,0,0]
	v_pk_fma_f32 v[172:173], v[172:173], v[182:183], v[182:183] op_sel_hi:[1,0,0]
	v_pk_fma_f32 v[174:175], v[174:175], v[182:183], v[182:183] op_sel_hi:[1,0,0]
	v_rcp_f32_e32 v168, v168
	v_rcp_f32_e32 v169, v169
	v_rcp_f32_e32 v170, v170
	v_rcp_f32_e32 v171, v171
	v_rcp_f32_e32 v172, v172
	v_rcp_f32_e32 v173, v173
	v_rcp_f32_e32 v174, v174
	v_rcp_f32_e32 v175, v175
	s_nop 0
	v_pk_mul_f32 v[92:93], v[92:93], v[168:169]
	v_pk_mul_f32 v[94:95], v[94:95], v[170:171]
	v_pk_mul_f32 v[84:85], v[84:85], v[172:173]
	v_pk_mul_f32 v[86:87], v[86:87], v[174:175]
	v_cvt_pk_bf16_f32 v176, v92, v93
	v_cvt_pk_bf16_f32 v177, v94, v95
	v_cvt_pk_bf16_f32 v178, v84, v85
	v_cvt_pk_bf16_f32 v179, v86, v87
	global_store_dwordx4 v[184:185], v[176:179], off
	v_lshl_add_u64 v[184:185], v[184:185], 0, s[34:35]
; __device__ __forceinline__ u32x2 pack4(const f32x4 v) { u32x2 w; w.x = cvt_pk_bf16(v[0], v[1]); w.y = cvt_pk_bf16(v[2], v[3]); return w; }
;     __device__ __forceinline__ void operator()(const f32x4 (&acc)[2][2][4][2], const Unit& u, int wr, int wc, int fr, int fq) const {
;     ...
;                 const float rs = rsv[ai][m];
;                 u32x2 w[2];
; #pragma unroll
;                 for (int n = 0; n < 2; ++n) {
;                     const f32x4 g = acc[ai][0][m][n] * rs, up = acc[ai][1][m][n] * rs; f32x4 o;
; #pragma unroll
;                     for (int j = 0; j < 4; ++j) { const float e = __builtin_amdgcn_exp2f(-g[j] * kLog2e); o[j] = g[j] * up[j] * __builtin_amdgcn_rcpf(1.0f + e); }
;                     w[n] = pack4(o);
;                 }
;                 *(u32x4_*)(H + (size_t)row * 2816 + u.pn * 128 + wc * 32 + fq * 8) = (u32x4_){w[0].x, w[0].y, w[1].x, w[1].y};
	v_mul_f32_e32 v180, 0xbfb8aa3b, v158
	v_mul_f32_e32 v182, v158, v158
	v_rcp_f32_e32 v182, v182
	v_pk_mul_f32 v[168:169], v[76:77], v[180:181] op_sel_hi:[1,0]
	v_pk_mul_f32 v[170:171], v[78:79], v[180:181] op_sel_hi:[1,0]
	v_pk_mul_f32 v[172:173], v[68:69], v[180:181] op_sel_hi:[1,0]
	v_pk_mul_f32 v[174:175], v[70:71], v[180:181] op_sel_hi:[1,0]
	v_exp_f32_e32 v168, v168
	v_exp_f32_e32 v169, v169
	v_exp_f32_e32 v170, v170
	v_exp_f32_e32 v171, v171
	v_exp_f32_e32 v172, v172
	v_exp_f32_e32 v173, v173
	v_exp_f32_e32 v174, v174
	v_exp_f32_e32 v175, v175
	v_pk_mul_f32 v[76:77], v[76:77], v[72:73]
	v_pk_mul_f32 v[78:79], v[78:79], v[74:75]
	v_pk_mul_f32 v[68:69], v[68:69], v[64:65]
	v_pk_mul_f32 v[70:71], v[70:71], v[66:67]
	v_pk_fma_f32 v[168:169], v[168:169], v[182:183], v[182:183] op_sel_hi:[1,0,0]
	v_pk_fma_f32 v[170:171], v[170:171], v[182:183], v[182:183] op_sel_hi:[1,0,0]
	v_pk_fma_f32 v[172:173], v[172:173], v[182:183], v[182:183] op_sel_hi:[1,0,0]
	v_pk_fma_f32 v[174:175], v[174:175], v[182:183], v[182:183] op_sel_hi:[1,0,0]
	v_rcp_f32_e32 v168, v168
	v_rcp_f32_e32 v169, v169
	v_rcp_f32_e32 v170, v170
	v_rcp_f32_e32 v171, v171
	v_rcp_f32_e32 v172, v172
	v_rcp_f32_e32 v173, v173
	v_rcp_f32_e32 v174, v174
	v_rcp_f32_e32 v175, v175
	s_nop 0
	v_pk_mul_f32 v[76:77], v[76:77], v[168:169]
	v_pk_mul_f32 v[78:79], v[78:79], v[170:171]
	v_pk_mul_f32 v[68:69], v[68:69], v[172:173]
	v_pk_mul_f32 v[70:71], v[70:71], v[174:175]
	v_cvt_pk_bf16_f32 v176, v76, v77
	v_cvt_pk_bf16_f32 v177, v78, v79
	v_cvt_pk_bf16_f32 v178, v68, v69
	v_cvt_pk_bf16_f32 v179, v70, v71
	global_store_dwordx4 v[184:185], v[176:179], off
	v_lshl_add_u64 v[184:185], v[184:185], 0, s[30:31]
	v_mul_f32_e32 v180, 0xbfb8aa3b, v156
	v_mul_f32_e32 v182, v156, v156
	v_rcp_f32_e32 v182, v182
	v_pk_mul_f32 v[168:169], v[60:61], v[180:181] op_sel_hi:[1,0]
	v_pk_mul_f32 v[170:171], v[62:63], v[180:181] op_sel_hi:[1,0]
	v_pk_mul_f32 v[172:173], v[52:53], v[180:181] op_sel_hi:[1,0]
	v_pk_mul_f32 v[174:175], v[54:55], v[180:181] op_sel_hi:[1,0]
	v_exp_f32_e32 v168, v168
	v_exp_f32_e32 v169, v169
	v_exp_f32_e32 v170, v170
	v_exp_f32_e32 v171, v171
	v_exp_f32_e32 v172, v172
	v_exp_f32_e32 v173, v173
	v_exp_f32_e32 v174, v174
	v_exp_f32_e32 v175, v175
	v_pk_mul_f32 v[60:61], v[60:61], v[56:57]
	v_pk_mul_f32 v[62:63], v[62:63], v[58:59]
	v_pk_mul_f32 v[52:53], v[52:53], v[48:49]
	v_pk_mul_f32 v[54:55], v[54:55], v[50:51]
	v_pk_fma_f32 v[168:169], v[168:169], v[182:183], v[182:183] op_sel_hi:[1,0,0]
	v_pk_fma_f32 v[170:171], v[170:171], v[182:183], v[182:183] op_sel_hi:[1,0,0]
	v_pk_fma_f32 v[172:173], v[172:173], v[182:183], v[182:183] op_sel_hi:[1,0,0]
	v_pk_fma_f32 v[174:175], v[174:175], v[182:183], v[182:183] op_sel_hi:[1,0,0]
	v_rcp_f32_e32 v168, v168
	v_rcp_f32_e32 v169, v169
	v_rcp_f32_e32 v170, v170
	v_rcp_f32_e32 v171, v171
	v_rcp_f32_e32 v172, v172
	v_rcp_f32_e32 v173, v173
	v_rcp_f32_e32 v174, v174
	v_rcp_f32_e32 v175, v175
	s_nop 0
	v_pk_mul_f32 v[60:61], v[60:61], v[168:169]
	v_pk_mul_f32 v[62:63], v[62:63], v[170:171]
	v_pk_mul_f32 v[52:53], v[52:53], v[172:173]
	v_pk_mul_f32 v[54:55], v[54:55], v[174:175]
	v_cvt_pk_bf16_f32 v176, v60, v61
	v_cvt_pk_bf16_f32 v177, v62, v63
	v_cvt_pk_bf16_f32 v178, v52, v53
	v_cvt_pk_bf16_f32 v179, v54, v55
	global_store_dwordx4 v[184:185], v[176:179], off
	v_lshl_add_u64 v[184:185], v[184:185], 0, s[34:35]
	v_mul_f32_e32 v180, 0xbfb8aa3b, v154
	v_mul_f32_e32 v182, v154, v154
	v_rcp_f32_e32 v182, v182
	v_pk_mul_f32 v[168:169], v[44:45], v[180:181] op_sel_hi:[1,0]
	v_pk_mul_f32 v[170:171], v[46:47], v[180:181] op_sel_hi:[1,0]
	v_pk_mul_f32 v[172:173], v[36:37], v[180:181] op_sel_hi:[1,0]
	v_pk_mul_f32 v[174:175], v[38:39], v[180:181] op_sel_hi:[1,0]
	v_exp_f32_e32 v168, v168
	v_exp_f32_e32 v169, v169
	v_exp_f32_e32 v170, v170
	v_exp_f32_e32 v171, v171
	v_exp_f32_e32 v172, v172
	v_exp_f32_e32 v173, v173
	v_exp_f32_e32 v174, v174
	v_exp_f32_e32 v175, v175
	v_pk_mul_f32 v[44:45], v[44:45], v[40:41]
	v_pk_mul_f32 v[46:47], v[46:47], v[42:43]
	v_pk_mul_f32 v[36:37], v[36:37], v[32:33]
	v_pk_mul_f32 v[38:39], v[38:39], v[34:35]
	v_pk_fma_f32 v[168:169], v[168:169], v[182:183], v[182:183] op_sel_hi:[1,0,0]
	v_pk_fma_f32 v[170:171], v[170:171], v[182:183], v[182:183] op_sel_hi:[1,0,0]
; __device__ __forceinline__ u32x2 pack4(const f32x4 v) { u32x2 w; w.x = cvt_pk_bf16(v[0], v[1]); w.y = cvt_pk_bf16(v[2], v[3]); return w; }
; #define PG8_BAR __builtin_amdgcn_s_barrier()
;     __device__ __forceinline__ void operator()(const f32x4 (&acc)[2][2][4][2], const Unit& u, int wr, int wc, int fr, int fq) const {
;     ...
;                 const float rs = rsv[ai][m];
;                 u32x2 w[2];
; #pragma unroll
;                 for (int n = 0; n < 2; ++n) {
;                     const f32x4 g = acc[ai][0][m][n] * rs, up = acc[ai][1][m][n] * rs; f32x4 o;
; #pragma unroll
;                     for (int j = 0; j < 4; ++j) { const float e = __builtin_amdgcn_exp2f(-g[j] * kLog2e); o[j] = g[j] * up[j] * __builtin_amdgcn_rcpf(1.0f + e); }
;                     w[n] = pack4(o);
;                 }
;                 *(u32x4_*)(H + (size_t)row * 2816 + u.pn * 128 + wc * 32 + fq * 8) = (u32x4_){w[0].x, w[0].y, w[1].x, w[1].y};
; template <class Epi, class Sched, bool ALIGN_EPI = false, bool SP2 = false>
; __device__ __forceinline__ void gemm_phase(PG8_LAS unsigned char* lds, const Gemm g, const Sched& S, const Epi& E) {
;     ...
;         if constexpr (!Epi::AFTER_DRAIN) { E(acc, cur, wr, wc, fr, fq); S.done(cur); }
;         if (!has_next) break;
; #pragma unroll
;         for (int a = 0; a < 2; ++a)
; #pragma unroll
;             for (int b = 0; b < 2; ++b)
; #pragma unroll
;                 for (int m = 0; m < 4; ++m)
; #pragma unroll
;                     for (int n = 0; n < 2; ++n) acc[a][b][m][n] = (f32x4){0.f, 0.f, 0.f, 0.f};
;         cur = nxt; cA = nA; cB = nB; ++ui;
;         if constexpr (ALIGN_EPI) { if (wr == 1) PG8_BAR; }
	v_pk_fma_f32 v[172:173], v[172:173], v[182:183], v[182:183] op_sel_hi:[1,0,0]
	v_pk_fma_f32 v[174:175], v[174:175], v[182:183], v[182:183] op_sel_hi:[1,0,0]
	v_rcp_f32_e32 v168, v168
	v_rcp_f32_e32 v169, v169
	v_rcp_f32_e32 v170, v170
	v_rcp_f32_e32 v171, v171
	v_rcp_f32_e32 v172, v172
	v_rcp_f32_e32 v173, v173
	v_rcp_f32_e32 v174, v174
	v_rcp_f32_e32 v175, v175
	s_nop 0
	v_pk_mul_f32 v[44:45], v[44:45], v[168:169]
	v_pk_mul_f32 v[46:47], v[46:47], v[170:171]
	v_pk_mul_f32 v[36:37], v[36:37], v[172:173]
	v_pk_mul_f32 v[38:39], v[38:39], v[174:175]
	v_cvt_pk_bf16_f32 v176, v44, v45
	v_cvt_pk_bf16_f32 v177, v46, v47
	v_cvt_pk_bf16_f32 v178, v36, v37
	v_cvt_pk_bf16_f32 v179, v38, v39
	global_store_dwordx4 v[184:185], v[176:179], off
	v_lshl_add_u64 v[184:185], v[184:185], 0, s[34:35]
	v_mul_f32_e32 v180, 0xbfb8aa3b, v150
	v_mul_f32_e32 v182, v150, v150
	v_rcp_f32_e32 v182, v182
	v_pk_mul_f32 v[168:169], v[28:29], v[180:181] op_sel_hi:[1,0]
	v_pk_mul_f32 v[170:171], v[30:31], v[180:181] op_sel_hi:[1,0]
	v_pk_mul_f32 v[172:173], v[20:21], v[180:181] op_sel_hi:[1,0]
	v_pk_mul_f32 v[174:175], v[22:23], v[180:181] op_sel_hi:[1,0]
	v_exp_f32_e32 v168, v168
	v_exp_f32_e32 v169, v169
	v_exp_f32_e32 v170, v170
	v_exp_f32_e32 v171, v171
	v_exp_f32_e32 v172, v172
	v_exp_f32_e32 v173, v173
	v_exp_f32_e32 v174, v174
	v_exp_f32_e32 v175, v175
	v_pk_mul_f32 v[28:29], v[28:29], v[24:25]
	v_pk_mul_f32 v[30:31], v[30:31], v[26:27]
	v_pk_mul_f32 v[20:21], v[20:21], v[16:17]
	v_pk_mul_f32 v[22:23], v[22:23], v[18:19]
	v_pk_fma_f32 v[168:169], v[168:169], v[182:183], v[182:183] op_sel_hi:[1,0,0]
	v_pk_fma_f32 v[170:171], v[170:171], v[182:183], v[182:183] op_sel_hi:[1,0,0]
	v_pk_fma_f32 v[172:173], v[172:173], v[182:183], v[182:183] op_sel_hi:[1,0,0]
	v_pk_fma_f32 v[174:175], v[174:175], v[182:183], v[182:183] op_sel_hi:[1,0,0]
	v_rcp_f32_e32 v168, v168
	v_rcp_f32_e32 v169, v169
	v_rcp_f32_e32 v170, v170
	v_rcp_f32_e32 v171, v171
	v_rcp_f32_e32 v172, v172
	v_rcp_f32_e32 v173, v173
	v_rcp_f32_e32 v174, v174
	v_rcp_f32_e32 v175, v175
	s_nop 0
	v_pk_mul_f32 v[28:29], v[28:29], v[168:169]
	v_pk_mul_f32 v[30:31], v[30:31], v[170:171]
	v_pk_mul_f32 v[20:21], v[20:21], v[172:173]
	v_pk_mul_f32 v[22:23], v[22:23], v[174:175]
	v_cvt_pk_bf16_f32 v176, v28, v29
	v_cvt_pk_bf16_f32 v177, v30, v31
	v_cvt_pk_bf16_f32 v178, v20, v21
	v_cvt_pk_bf16_f32 v179, v22, v23
	global_store_dwordx4 v[184:185], v[176:179], off
	v_lshl_add_u64 v[184:185], v[184:185], 0, s[34:35]
	v_mul_f32_e32 v180, 0xbfb8aa3b, v146
	v_mul_f32_e32 v182, v146, v146
	v_rcp_f32_e32 v182, v182
	v_pk_mul_f32 v[168:169], v[12:13], v[180:181] op_sel_hi:[1,0]
	v_pk_mul_f32 v[170:171], v[14:15], v[180:181] op_sel_hi:[1,0]
	v_pk_mul_f32 v[172:173], v[4:5], v[180:181] op_sel_hi:[1,0]
	v_pk_mul_f32 v[174:175], v[6:7], v[180:181] op_sel_hi:[1,0]
	v_exp_f32_e32 v168, v168
	v_exp_f32_e32 v169, v169
	v_exp_f32_e32 v170, v170
	v_exp_f32_e32 v171, v171
	v_exp_f32_e32 v172, v172
	v_exp_f32_e32 v173, v173
	v_exp_f32_e32 v174, v174
	v_exp_f32_e32 v175, v175
	v_pk_mul_f32 v[12:13], v[12:13], v[8:9]
	v_pk_mul_f32 v[14:15], v[14:15], v[10:11]
	v_pk_mul_f32 v[4:5], v[4:5], v[0:1]
	v_pk_mul_f32 v[6:7], v[6:7], v[2:3]
	v_pk_fma_f32 v[168:169], v[168:169], v[182:183], v[182:183] op_sel_hi:[1,0,0]
	v_pk_fma_f32 v[170:171], v[170:171], v[182:183], v[182:183] op_sel_hi:[1,0,0]
	v_pk_fma_f32 v[172:173], v[172:173], v[182:183], v[182:183] op_sel_hi:[1,0,0]
	v_pk_fma_f32 v[174:175], v[174:175], v[182:183], v[182:183] op_sel_hi:[1,0,0]
	v_rcp_f32_e32 v168, v168
	v_rcp_f32_e32 v169, v169
	v_rcp_f32_e32 v170, v170
	v_rcp_f32_e32 v171, v171
	v_rcp_f32_e32 v172, v172
	v_rcp_f32_e32 v173, v173
	v_rcp_f32_e32 v174, v174
	v_rcp_f32_e32 v175, v175
	s_nop 0
	v_pk_mul_f32 v[12:13], v[12:13], v[168:169]
	v_pk_mul_f32 v[14:15], v[14:15], v[170:171]
	v_pk_mul_f32 v[4:5], v[4:5], v[172:173]
	v_pk_mul_f32 v[6:7], v[6:7], v[174:175]
	v_cvt_pk_bf16_f32 v176, v12, v13
	v_cvt_pk_bf16_f32 v177, v14, v15
	v_cvt_pk_bf16_f32 v178, v4, v5
	v_cvt_pk_bf16_f32 v179, v6, v7
	global_store_dwordx4 v[184:185], v[176:179], off
	s_mov_b64 s[30:31], -1
	s_cbranch_vccnz .LBB0_182
	s_mov_b32 s92, 0
	s_andn2_b64 vcc, exec, s[28:29]
	s_cbranch_vccnz .LBB0_181
	s_mov_b32 s92, 1
	s_branch .LBB0_181
